# P2 end balance: the 64 nine-unit workgroups convert 20 w_gate|w_up tiles each instead of 22 (they were ~5 us over the ten-unit workgroups); the 128 displaced tiles go to the odd ten-unit workgroups, w
# baseline (speedup 1.0000x reference)
.LBB0_526:
	s_cmpk_lt_i32 s96, 0xc0
	s_cbranch_scc1 .Lq2t_light
	s_add_i32 s10, s96, 0xffffff40
	s_movk_i32 s2, 0x500
	s_movk_i32 s3, 64
	s_branch .Lq2t_go
.Lq2t_light:
	s_bitcmp0_b32 s96, 0
	s_cbranch_scc1 .LBB0_535
	s_lshr_b32 s10, s96, 1
	s_addk_i32 s10, 0x500
	s_movk_i32 s2, 0x580
	s_movk_i32 s3, 0x60
.Lq2t_go:
	s_load_dwordx4 s[16:19], s[0:1], 0xa8
	s_add_u32 s4, s36, 0x1bd3c000
	v_mov_b32_e32 v54, v184
	s_addc_u32 s5, s37, 0
	s_lshl_b32 s6, s10, 2
	v_and_b32_e32 v0, 0x7f, v54
	v_and_b32_e32 v5, 63, v54
	s_and_b32 s6, s6, 0x3ffc0
	s_waitcnt lgkmcnt(0)
	v_mov_b32_e32 v1, s19
	v_mov_b32_e32 v3, s17
	v_cmp_gt_u32_e32 vcc, 64, v0
	s_lshl_b32 s8, s10, 7
	v_ashrrev_i32_e32 v4, 7, v54
	v_or_b32_e32 v2, s6, v5
	v_cndmask_b32_e32 v1, v1, v3, vcc
	v_mov_b32_e32 v0, s18
	v_mov_b32_e32 v3, s16
	s_and_b32 s6, s8, 0x780
	v_cndmask_b32_e32 v0, v0, v3, vcc
	v_add_u32_e32 v3, s6, v4
	s_movk_i32 s9, 0x5800
	v_mad_i64_i32 v[6:7], s[6:7], v3, s9, v[0:1]
	v_lshlrev_b32_e32 v2, 2, v2
	v_mov_b32_e32 v3, 0
	v_lshl_add_u64 v[22:23], v[6:7], 0, v[2:3]
	s_mov_b32 s6, 0x16000
	v_add_co_u32_e32 v14, vcc, s6, v22
	s_mov_b32 s6, 0x2c000
	s_waitcnt vmcnt(0)
	v_addc_co_u32_e32 v15, vcc, 0, v23, vcc
	v_add_co_u32_e32 v16, vcc, s6, v22
	s_mov_b32 s6, 0x42000
	s_nop 0
	v_addc_co_u32_e32 v17, vcc, 0, v23, vcc
	v_add_co_u32_e32 v18, vcc, s6, v22
	s_mov_b32 s6, 0x58000
	s_nop 0
	v_addc_co_u32_e32 v19, vcc, 0, v23, vcc
	v_add_co_u32_e32 v20, vcc, s6, v22
	s_mov_b32 s6, 0x6e000
	s_nop 0
	v_addc_co_u32_e32 v21, vcc, 0, v23, vcc
	v_add_co_u32_e32 v24, vcc, s6, v22
	s_mov_b32 s6, 0x84000
	s_nop 0
	v_addc_co_u32_e32 v25, vcc, 0, v23, vcc
	v_add_co_u32_e32 v26, vcc, s6, v22
	s_mov_b32 s6, 0x9a000
	s_nop 0
	v_addc_co_u32_e32 v27, vcc, 0, v23, vcc
	v_add_co_u32_e32 v28, vcc, s6, v22
	s_mov_b32 s6, 0xb0000
	s_nop 0
	v_addc_co_u32_e32 v29, vcc, 0, v23, vcc
	global_load_dword v6, v[22:23], off nt
	global_load_dword v7, v[14:15], off nt
	global_load_dword v8, v[16:17], off nt
	global_load_dword v9, v[18:19], off nt
	global_load_dword v10, v[20:21], off nt
	global_load_dword v11, v[24:25], off nt
	global_load_dword v12, v[26:27], off nt
	global_load_dword v13, v[28:29], off nt
	v_add_co_u32_e32 v24, vcc, s6, v22
	s_mov_b32 s6, 0xc6000
	s_nop 0
	v_addc_co_u32_e32 v25, vcc, 0, v23, vcc
	v_add_co_u32_e32 v26, vcc, s6, v22
	s_mov_b32 s6, 0xdc000
	s_nop 0
	v_addc_co_u32_e32 v27, vcc, 0, v23, vcc
	v_add_co_u32_e32 v28, vcc, s6, v22
	s_mov_b32 s6, 0xf2000
	s_nop 0
	v_addc_co_u32_e32 v29, vcc, 0, v23, vcc
	v_add_co_u32_e32 v30, vcc, s6, v22
	s_mov_b32 s6, 0x108000
	s_nop 0
	v_addc_co_u32_e32 v31, vcc, 0, v23, vcc
	v_add_co_u32_e32 v32, vcc, s6, v22
	s_mov_b32 s6, 0x11e000
	s_nop 0
	v_addc_co_u32_e32 v33, vcc, 0, v23, vcc
	v_add_co_u32_e32 v34, vcc, s6, v22
	s_mov_b32 s6, 0x134000
	s_nop 0
	v_addc_co_u32_e32 v35, vcc, 0, v23, vcc
	v_add_co_u32_e32 v36, vcc, s6, v22
	s_mov_b32 s6, 0x14a000
	s_nop 0
	v_addc_co_u32_e32 v37, vcc, 0, v23, vcc
	v_add_co_u32_e32 v38, vcc, s6, v22
	s_mov_b32 s6, 0x160000
	s_nop 0
	v_addc_co_u32_e32 v39, vcc, 0, v23, vcc
	global_load_dword v14, v[24:25], off nt
	global_load_dword v15, v[26:27], off nt
	global_load_dword v16, v[28:29], off nt
	global_load_dword v17, v[30:31], off nt
	global_load_dword v18, v[32:33], off nt
	global_load_dword v19, v[34:35], off nt
	global_load_dword v20, v[36:37], off nt
	global_load_dword v21, v[38:39], off nt
	v_add_co_u32_e32 v24, vcc, s6, v22
	s_mov_b32 s6, 0x176000
	s_nop 0
	v_addc_co_u32_e32 v25, vcc, 0, v23, vcc
	v_add_co_u32_e32 v26, vcc, s6, v22
	s_mov_b32 s6, 0x18c000
	s_nop 0
	v_addc_co_u32_e32 v27, vcc, 0, v23, vcc
	v_add_co_u32_e32 v28, vcc, s6, v22
	s_mov_b32 s6, 0x1a2000
	s_nop 0
	v_addc_co_u32_e32 v29, vcc, 0, v23, vcc
	v_add_co_u32_e32 v30, vcc, s6, v22
	s_mov_b32 s6, 0x1b8000
	s_nop 0
	v_addc_co_u32_e32 v31, vcc, 0, v23, vcc
	v_add_co_u32_e32 v40, vcc, s6, v22
	s_mov_b32 s6, 0x1ce000
	s_nop 0
	v_addc_co_u32_e32 v41, vcc, 0, v23, vcc
	v_add_co_u32_e32 v42, vcc, s6, v22
	s_mov_b32 s6, 0x1e4000
	s_nop 0
	v_addc_co_u32_e32 v43, vcc, 0, v23, vcc
	v_add_co_u32_e32 v44, vcc, s6, v22
	s_mov_b32 s6, 0x1fa000
	s_nop 0
	v_addc_co_u32_e32 v45, vcc, 0, v23, vcc
	v_add_co_u32_e32 v46, vcc, s6, v22
	s_mov_b32 s6, 0x210000
	s_nop 0
	v_addc_co_u32_e32 v47, vcc, 0, v23, vcc
	global_load_dword v32, v[24:25], off nt
	global_load_dword v33, v[26:27], off nt
	global_load_dword v34, v[28:29], off nt
	global_load_dword v35, v[30:31], off nt
	global_load_dword v36, v[40:41], off nt
	global_load_dword v37, v[42:43], off nt
	global_load_dword v38, v[44:45], off nt
	global_load_dword v39, v[46:47], off nt
	v_add_co_u32_e32 v24, vcc, s6, v22
	s_mov_b32 s6, 0x226000
	s_nop 0
	v_addc_co_u32_e32 v25, vcc, 0, v23, vcc
	v_add_co_u32_e32 v26, vcc, s6, v22
	s_mov_b32 s6, 0x23c000
	s_nop 0
	v_addc_co_u32_e32 v27, vcc, 0, v23, vcc
	v_add_co_u32_e32 v28, vcc, s6, v22
	s_mov_b32 s6, 0x252000
	s_nop 0
	v_addc_co_u32_e32 v29, vcc, 0, v23, vcc
	v_add_co_u32_e32 v30, vcc, s6, v22
	s_mov_b32 s6, 0x268000
	s_nop 0
	v_addc_co_u32_e32 v31, vcc, 0, v23, vcc
	v_add_co_u32_e32 v48, vcc, s6, v22
	s_mov_b32 s6, 0x27e000
	s_nop 0
	v_addc_co_u32_e32 v49, vcc, 0, v23, vcc
	v_add_co_u32_e32 v50, vcc, s6, v22
	s_mov_b32 s6, 0x294000
	s_nop 0
	v_addc_co_u32_e32 v51, vcc, 0, v23, vcc
	v_add_co_u32_e32 v52, vcc, s6, v22
	s_mov_b32 s6, 0x2aa000
	s_nop 0
	v_addc_co_u32_e32 v53, vcc, 0, v23, vcc
	v_add_co_u32_e32 v22, vcc, s6, v22
	v_lshlrev_b32_e32 v2, 1, v54
	s_nop 0
	v_addc_co_u32_e32 v23, vcc, 0, v23, vcc
	global_load_dword v40, v[24:25], off nt
	global_load_dword v41, v[26:27], off nt
	global_load_dword v42, v[28:29], off nt
	global_load_dword v43, v[30:31], off nt
	global_load_dword v44, v[48:49], off nt
	global_load_dword v45, v[50:51], off nt
	global_load_dword v46, v[52:53], off nt
	global_load_dword v47, v[22:23], off nt
	v_lshrrev_b32_e32 v22, 4, v54
	v_and_b32_e32 v2, 0x78, v2
	v_and_b32_e32 v22, 4, v22
	v_and_b32_e32 v23, 3, v54
	v_or3_b32 v30, v22, v23, v2
	v_lshlrev_b32_e32 v2, 3, v54
	v_add_u32_e32 v24, 0x200, v54
	v_add_u32_e32 v26, 0x400, v54
	v_add_u32_e32 v28, 0x600, v54
	v_and_b32_e32 v2, 0x78, v2
	v_ashrrev_i32_e32 v22, 4, v54
	s_movk_i32 s6, 0x110
	v_ashrrev_i32_e32 v24, 4, v24
	v_ashrrev_i32_e32 v26, 4, v26
	v_ashrrev_i32_e32 v28, 4, v28
	s_lshl_b32 s12, s3, 7
	s_mov_b32 s11, 0
	v_mul_lo_u32 v23, v22, s6
	v_mul_lo_u32 v25, v24, s6
	v_mul_lo_u32 v27, v26, s6
	v_mul_lo_u32 v29, v28, s6
	v_mul_u32_u24_e32 v30, 0x110, v30
	v_add_u32_e32 v31, s12, v4
	s_movk_i32 s13, 0x7fff
	v_lshlrev_b32_e32 v2, 1, v2
	s_barrier
	s_branch .LBB0_530
